# GEMM2 and GEMM5: every other CU of each XCD starts the phase 5 us late (epilogue/main-loop overlap across CUs); compute-dtype header comment added
# speedup vs baseline: 1.0150x; 1.0038x over previous
.LBB0_877:
	s_cmp_lt_i32 s64, 10
	s_cselect_b64 s[4:5], -1, 0
	s_and_b64 s[0:1], s[4:5], s[0:1]
	s_and_b64 s[0:1], s[0:1], s[6:7]
	s_andn2_b64 vcc, exec, s[0:1]
	s_cbranch_vccnz .LBB0_884
	s_and_b32 s0, s62, 7
	s_cmp_lg_u32 s0, 0
	s_cselect_b64 s[0:1], -1, 0
	s_ashr_i32 s3, s62, 3
	s_add_u32 s8, s96, 0xda0000
	s_addc_u32 s9, s97, 0
	s_add_u32 s10, s96, 0x13a0000
	s_addc_u32 s11, s97, 0
	s_abs_i32 s12, s62
	v_cvt_f32_u32_e32 v1, s12
	v_cndmask_b32_e64 v0, 0, 1, s[0:1]
	s_sub_i32 s0, 0, s12
	s_lshl_b32 s15, s62, 3
	v_rcp_iflag_f32_e32 v1, v1
	s_ashr_i32 s13, s62, 31
	s_sub_i32 s14, 0, s62
	s_lshl_b32 s16, s2, 3
	v_mul_f32_e32 v1, 0x4f7ffffe, v1
	v_cvt_u32_f32_e32 v1, v1
	s_sub_i32 s17, 0, s15
	v_mov_b32_e32 v65, 0
	s_movk_i32 s19, 0x90
	v_readfirstlane_b32 s1, v1
	s_mul_i32 s0, s0, s1
	s_mul_hi_u32 s0, s1, s0
	s_add_i32 s18, s1, s0
	v_cmp_ne_u32_e64 s[0:1], 1, v0
	s_mov_b32 s20, 0xfffffc0
	s_mov_b32 s21, 0x20000
	s_mov_b32 s22, 0x40000
	s_mov_b32 s23, 0x60000
	s_movk_i32 s24, 0xff00
	s_movk_i32 s25, 0x410
	s_movk_i32 s26, 0x2000
	s_bitcmp1_b32 s2, 3
	s_cbranch_scc0 .Lskew_done_g5
	s_memrealtime s[98:99]
	s_waitcnt lgkmcnt(0)
	s_add_u32 s100, s98, 500
.Lskew_loop_g5:
	s_sleep 8
	s_memrealtime s[98:99]
	s_waitcnt lgkmcnt(0)
	s_sub_u32 s99, s98, s100
	s_cmp_lt_i32 s99, 0
	s_cbranch_scc1 .Lskew_loop_g5
.Lskew_done_g5:
	s_branch .LBB0_880
.LBB0_879:
	s_ashr_i32 s5, s4, 31
	s_lshr_b32 s5, s5, 30
	s_add_i32 s5, s4, s5
	s_and_b32 s5, s5, 0xfffffc
	s_sub_i32 s4, s4, s5
	s_lshl_b32 s6, s4, 8
	s_ashr_i32 s7, s6, 31
	v_mov_b32_e32 v48, v212
	s_lshl_b32 s4, s27, 7
	s_lshl_b64 s[28:29], s[6:7], 11
	s_add_u32 s28, s8, s28
	v_ashrrev_i32_e32 v24, 3, v48
	v_ashrrev_i32_e32 v25, 31, v24
	s_addc_u32 s29, s9, s29
	v_lshlrev_b64 v[0:1], 11, v[24:25]
	v_lshlrev_b32_e32 v4, 4, v48
	v_lshl_add_u64 v[2:3], s[28:29], 0, v[0:1]
	v_and_b32_e32 v64, 0x70, v4
	v_lshl_add_u64 v[70:71], v[2:3], 0, v[64:65]
	v_add_co_u32_e32 v74, vcc, s21, v70
	s_ashr_i32 s5, s4, 31
	s_nop 0
	v_addc_co_u32_e32 v75, vcc, 0, v71, vcc
	s_lshl_b64 s[30:31], s[4:5], 11
	v_add_co_u32_e32 v76, vcc, s22, v70
	s_add_u32 s30, s10, s30
	s_nop 0
	v_addc_co_u32_e32 v77, vcc, 0, v71, vcc
	s_addc_u32 s31, s11, s31
	v_add_co_u32_e32 v78, vcc, s23, v70
	v_lshl_add_u64 v[0:1], s[30:31], 0, v[0:1]
	s_nop 0
	v_addc_co_u32_e32 v79, vcc, 0, v71, vcc
	v_lshl_add_u64 v[72:73], v[0:1], 0, v[64:65]
	global_load_dwordx4 v[0:3], v[70:71], off
	global_load_dwordx4 v[4:7], v[74:75], off
	global_load_dwordx4 v[8:11], v[76:77], off
	global_load_dwordx4 v[12:15], v[78:79], off
	global_load_dwordx4 v[16:19], v[72:73], off
	v_add_co_u32_e32 v80, vcc, s21, v72
	v_mad_u64_u32 v[68:69], s[28:29], v24, s19, v[64:65]
	s_nop 0
	v_addc_co_u32_e32 v81, vcc, 0, v73, vcc
	global_load_dwordx4 v[20:23], v[80:81], off
	global_load_dwordx4 v[24:27], v[70:71], off offset:128
	global_load_dwordx4 v[28:31], v[74:75], off offset:128
	global_load_dwordx4 v[32:35], v[78:79], off offset:128
	global_load_dwordx4 v[84:87], v[74:75], off offset:256
	global_load_dwordx4 v[36:39], v[76:77], off offset:128
	global_load_dwordx4 v[88:91], v[76:77], off offset:256
	global_load_dwordx4 v[92:95], v[70:71], off offset:256
	global_load_dwordx4 v[40:43], v[72:73], off offset:128
	global_load_dwordx4 v[96:99], v[72:73], off offset:256
	global_load_dwordx4 v[100:103], v[78:79], off offset:256
	global_load_dwordx4 v[44:47], v[80:81], off offset:128
	global_load_dwordx4 v[104:107], v[80:81], off offset:256
	v_add_u32_e32 v83, 0x12000, v68
	s_waitcnt vmcnt(17)
	ds_write_b128 v68, v[0:3]
	s_waitcnt vmcnt(16)
	ds_write_b128 v68, v[4:7] offset:9216
	s_waitcnt vmcnt(15)
	ds_write_b128 v68, v[8:11] offset:18432
	s_waitcnt vmcnt(14)
	ds_write_b128 v68, v[12:15] offset:27648
	s_waitcnt vmcnt(13)
	ds_write_b128 v68, v[16:19] offset:36864
	s_waitcnt vmcnt(12)
	ds_write_b128 v68, v[20:23] offset:46080
	s_waitcnt lgkmcnt(0)
	s_barrier
	global_load_dwordx4 v[108:111], v[74:75], off offset:384
	global_load_dwordx4 v[112:115], v[76:77], off offset:384
	global_load_dwordx4 v[116:119], v[70:71], off offset:384
	global_load_dwordx4 v[120:123], v[72:73], off offset:384
	global_load_dwordx4 v[124:127], v[78:79], off offset:384
	global_load_dwordx4 v[128:131], v[80:81], off offset:384
	v_and_b32_e32 v0, 31, v48
	v_lshrrev_b32_e32 v1, 1, v48
	v_and_or_b32 v2, v1, s20, v0
	v_and_b32_e32 v0, 16, v1
	v_and_b32_e32 v1, 0x5f, v48
	v_mad_u32_u24 v69, v1, s19, v0
	v_add_u32_e32 v64, 0x12000, v69
	s_waitcnt vmcnt(17)
	ds_write_b128 v83, v[24:27]
	s_waitcnt vmcnt(16)
	ds_write_b128 v83, v[28:31] offset:9216
	s_waitcnt vmcnt(13)
	ds_write_b128 v83, v[36:39] offset:18432
	ds_write_b128 v83, v[32:35] offset:27648
	s_waitcnt vmcnt(10)
	ds_write_b128 v83, v[40:43] offset:36864
	s_waitcnt vmcnt(7)
	ds_write_b128 v83, v[44:47] offset:46080
	v_mad_u64_u32 v[66:67], s[28:29], v2, s19, v[0:1]
	ds_read_b128 v[0:3], v69 offset:36864
	ds_read_b128 v[132:135], v69 offset:36896
	ds_read_b128 v[4:7], v69 offset:41472
	ds_read_b128 v[136:139], v69 offset:41504
	ds_read_b128 v[8:11], v66
	ds_read_b128 v[140:143], v66 offset:32
	ds_read_b128 v[12:15], v66 offset:4608
	ds_read_b128 v[144:147], v66 offset:4640
	s_setprio 1
	s_waitcnt lgkmcnt(3)
	v_mfma_f32_32x32x16_bf16 v[48:63], v[8:11], v[0:3], 0
	v_mfma_f32_32x32x16_bf16 v[16:31], v[8:11], v[4:7], 0
	s_waitcnt lgkmcnt(1)
	v_mfma_f32_32x32x16_bf16 v[32:47], v[12:15], v[0:3], 0
	v_mfma_f32_32x32x16_bf16 v[0:15], v[12:15], v[4:7], 0
	s_setprio 0
	ds_read_b128 v[148:151], v69 offset:36928
	ds_read_b128 v[152:155], v69 offset:41536
	ds_read_b128 v[156:159], v66 offset:64
	ds_read_b128 v[160:163], v66 offset:4672
	s_setprio 1
	v_mfma_f32_32x32x16_bf16 v[48:63], v[140:143], v[132:135], v[48:63]
	v_mfma_f32_32x32x16_bf16 v[16:31], v[140:143], v[136:139], v[16:31]
	s_waitcnt lgkmcnt(4)
	v_mfma_f32_32x32x16_bf16 v[32:47], v[144:147], v[132:135], v[32:47]
	v_mfma_f32_32x32x16_bf16 v[0:15], v[144:147], v[136:139], v[0:15]
	s_setprio 0
	ds_read_b128 v[132:135], v69 offset:36960
	ds_read_b128 v[136:139], v69 offset:41568
	ds_read_b128 v[140:143], v66 offset:96
	ds_read_b128 v[144:147], v66 offset:4704
	s_setprio 1
	s_waitcnt lgkmcnt(5)
	v_mfma_f32_32x32x16_bf16 v[48:63], v[156:159], v[148:151], v[48:63]
	v_mfma_f32_32x32x16_bf16 v[16:31], v[156:159], v[152:155], v[16:31]
	s_waitcnt lgkmcnt(4)
	v_mfma_f32_32x32x16_bf16 v[32:47], v[160:163], v[148:151], v[32:47]
	v_mfma_f32_32x32x16_bf16 v[0:15], v[160:163], v[152:155], v[0:15]
	s_setprio 0
	s_setprio 1
	s_waitcnt lgkmcnt(1)
	v_mfma_f32_32x32x16_bf16 v[48:63], v[140:143], v[132:135], v[48:63]
	v_mfma_f32_32x32x16_bf16 v[16:31], v[140:143], v[136:139], v[16:31]
	s_waitcnt lgkmcnt(0)
	v_mfma_f32_32x32x16_bf16 v[32:47], v[144:147], v[132:135], v[32:47]
	v_mfma_f32_32x32x16_bf16 v[0:15], v[144:147], v[136:139], v[0:15]
	s_setprio 0
	s_barrier
	global_load_dwordx4 v[132:135], v[74:75], off offset:512
	global_load_dwordx4 v[136:139], v[76:77], off offset:512
	global_load_dwordx4 v[140:143], v[70:71], off offset:512
	global_load_dwordx4 v[144:147], v[72:73], off offset:512
	global_load_dwordx4 v[148:151], v[78:79], off offset:512
	global_load_dwordx4 v[152:155], v[80:81], off offset:512
	ds_write_b128 v68, v[92:95]
	ds_write_b128 v68, v[84:87] offset:9216
	ds_write_b128 v68, v[88:91] offset:18432
	ds_write_b128 v68, v[100:103] offset:27648
	ds_write_b128 v68, v[96:99] offset:36864
	s_waitcnt vmcnt(12)
	ds_write_b128 v68, v[104:107] offset:46080
	v_add_u32_e32 v67, 0x12000, v66
	ds_read_b128 v[84:87], v64 offset:36864
	ds_read_b128 v[88:91], v64 offset:36896
	ds_read_b128 v[92:95], v64 offset:41472
	ds_read_b128 v[96:99], v64 offset:41504
	ds_read_b128 v[100:103], v67
	ds_read_b128 v[104:107], v67 offset:32
	ds_read_b128 v[156:159], v67 offset:4608
	ds_read_b128 v[160:163], v67 offset:4640
	s_setprio 1
	s_waitcnt lgkmcnt(3)
	v_mfma_f32_32x32x16_bf16 v[48:63], v[100:103], v[84:87], v[48:63]
	v_mfma_f32_32x32x16_bf16 v[16:31], v[100:103], v[92:95], v[16:31]
	s_waitcnt lgkmcnt(1)
	v_mfma_f32_32x32x16_bf16 v[32:47], v[156:159], v[84:87], v[32:47]
	v_mfma_f32_32x32x16_bf16 v[0:15], v[156:159], v[92:95], v[0:15]
	s_setprio 0
	ds_read_b128 v[84:87], v64 offset:36928
	ds_read_b128 v[92:95], v64 offset:41536
	ds_read_b128 v[100:103], v67 offset:64
	ds_read_b128 v[156:159], v67 offset:4672
	s_setprio 1
	v_mfma_f32_32x32x16_bf16 v[48:63], v[104:107], v[88:91], v[48:63]
	v_mfma_f32_32x32x16_bf16 v[16:31], v[104:107], v[96:99], v[16:31]
	s_waitcnt lgkmcnt(4)
	v_mfma_f32_32x32x16_bf16 v[32:47], v[160:163], v[88:91], v[32:47]
	v_mfma_f32_32x32x16_bf16 v[0:15], v[160:163], v[96:99], v[0:15]
	s_setprio 0
	ds_read_b128 v[88:91], v64 offset:36960
	ds_read_b128 v[96:99], v64 offset:41568
	ds_read_b128 v[104:107], v67 offset:96
	ds_read_b128 v[160:163], v67 offset:4704
	s_setprio 1
	s_waitcnt lgkmcnt(5)
	v_mfma_f32_32x32x16_bf16 v[48:63], v[100:103], v[84:87], v[48:63]
	v_mfma_f32_32x32x16_bf16 v[16:31], v[100:103], v[92:95], v[16:31]
	s_waitcnt lgkmcnt(4)
	v_mfma_f32_32x32x16_bf16 v[32:47], v[156:159], v[84:87], v[32:47]
	v_mfma_f32_32x32x16_bf16 v[0:15], v[156:159], v[92:95], v[0:15]
	s_setprio 0
	s_setprio 1
	s_waitcnt lgkmcnt(1)
	v_mfma_f32_32x32x16_bf16 v[48:63], v[104:107], v[88:91], v[48:63]
	v_mfma_f32_32x32x16_bf16 v[16:31], v[104:107], v[96:99], v[16:31]
	s_waitcnt lgkmcnt(0)
	v_mfma_f32_32x32x16_bf16 v[32:47], v[160:163], v[88:91], v[32:47]
	v_mfma_f32_32x32x16_bf16 v[0:15], v[160:163], v[96:99], v[0:15]
	s_setprio 0
	s_barrier
	global_load_dwordx4 v[84:87], v[74:75], off offset:640
	global_load_dwordx4 v[88:91], v[76:77], off offset:640
	global_load_dwordx4 v[92:95], v[70:71], off offset:640
	global_load_dwordx4 v[96:99], v[72:73], off offset:640
	global_load_dwordx4 v[100:103], v[78:79], off offset:640
	global_load_dwordx4 v[104:107], v[80:81], off offset:640
	s_waitcnt vmcnt(15)
	ds_write_b128 v83, v[116:119]
	ds_write_b128 v83, v[108:111] offset:9216
	ds_write_b128 v83, v[112:115] offset:18432
	s_waitcnt vmcnt(13)
	ds_write_b128 v83, v[124:127] offset:27648
	ds_write_b128 v83, v[120:123] offset:36864
	s_waitcnt vmcnt(12)
	ds_write_b128 v83, v[128:131] offset:46080
	ds_read_b128 v[108:111], v69 offset:36864
	ds_read_b128 v[112:115], v69 offset:36896
	ds_read_b128 v[116:119], v69 offset:41472
	ds_read_b128 v[120:123], v69 offset:41504
	ds_read_b128 v[124:127], v66
	ds_read_b128 v[128:131], v66 offset:32
	ds_read_b128 v[156:159], v66 offset:4608
	ds_read_b128 v[160:163], v66 offset:4640
	s_setprio 1
	s_waitcnt lgkmcnt(3)
	v_mfma_f32_32x32x16_bf16 v[48:63], v[124:127], v[108:111], v[48:63]
	v_mfma_f32_32x32x16_bf16 v[16:31], v[124:127], v[116:119], v[16:31]
	s_waitcnt lgkmcnt(1)
	v_mfma_f32_32x32x16_bf16 v[32:47], v[156:159], v[108:111], v[32:47]
	v_mfma_f32_32x32x16_bf16 v[0:15], v[156:159], v[116:119], v[0:15]
	s_setprio 0
	ds_read_b128 v[108:111], v69 offset:36928
	ds_read_b128 v[116:119], v69 offset:41536
	ds_read_b128 v[124:127], v66 offset:64
	ds_read_b128 v[156:159], v66 offset:4672
	s_setprio 1
	v_mfma_f32_32x32x16_bf16 v[48:63], v[128:131], v[112:115], v[48:63]
	v_mfma_f32_32x32x16_bf16 v[16:31], v[128:131], v[120:123], v[16:31]
	s_waitcnt lgkmcnt(4)
	v_mfma_f32_32x32x16_bf16 v[32:47], v[160:163], v[112:115], v[32:47]
	v_mfma_f32_32x32x16_bf16 v[0:15], v[160:163], v[120:123], v[0:15]
	s_setprio 0
	ds_read_b128 v[112:115], v69 offset:36960
	ds_read_b128 v[120:123], v69 offset:41568
	ds_read_b128 v[128:131], v66 offset:96
	ds_read_b128 v[160:163], v66 offset:4704
	s_setprio 1
	s_waitcnt lgkmcnt(5)
	v_mfma_f32_32x32x16_bf16 v[48:63], v[124:127], v[108:111], v[48:63]
	v_mfma_f32_32x32x16_bf16 v[16:31], v[124:127], v[116:119], v[16:31]
	s_waitcnt lgkmcnt(4)
	v_mfma_f32_32x32x16_bf16 v[32:47], v[156:159], v[108:111], v[32:47]
	v_mfma_f32_32x32x16_bf16 v[0:15], v[156:159], v[116:119], v[0:15]
	s_setprio 0
	s_setprio 1
	s_waitcnt lgkmcnt(1)
	v_mfma_f32_32x32x16_bf16 v[48:63], v[128:131], v[112:115], v[48:63]
	v_mfma_f32_32x32x16_bf16 v[16:31], v[128:131], v[120:123], v[16:31]
	s_waitcnt lgkmcnt(0)
	v_mfma_f32_32x32x16_bf16 v[32:47], v[160:163], v[112:115], v[32:47]
	v_mfma_f32_32x32x16_bf16 v[0:15], v[160:163], v[120:123], v[0:15]
	s_setprio 0
	s_barrier
	global_load_dwordx4 v[108:111], v[74:75], off offset:768
	global_load_dwordx4 v[112:115], v[76:77], off offset:768
	global_load_dwordx4 v[116:119], v[70:71], off offset:768
	global_load_dwordx4 v[120:123], v[72:73], off offset:768
	global_load_dwordx4 v[124:127], v[78:79], off offset:768
	global_load_dwordx4 v[128:131], v[80:81], off offset:768
	s_waitcnt vmcnt(15)
	ds_write_b128 v68, v[140:143]
	ds_write_b128 v68, v[132:135] offset:9216
	ds_write_b128 v68, v[136:139] offset:18432
	s_waitcnt vmcnt(13)
	ds_write_b128 v68, v[148:151] offset:27648
	ds_write_b128 v68, v[144:147] offset:36864
	s_waitcnt vmcnt(12)
	ds_write_b128 v68, v[152:155] offset:46080
	ds_read_b128 v[132:135], v64 offset:36864
	ds_read_b128 v[136:139], v64 offset:36896
	ds_read_b128 v[140:143], v64 offset:41472
	ds_read_b128 v[144:147], v64 offset:41504
	ds_read_b128 v[148:151], v67
	ds_read_b128 v[152:155], v67 offset:32
	ds_read_b128 v[156:159], v67 offset:4608
	ds_read_b128 v[160:163], v67 offset:4640
	s_setprio 1
	s_waitcnt lgkmcnt(3)
	v_mfma_f32_32x32x16_bf16 v[48:63], v[148:151], v[132:135], v[48:63]
	v_mfma_f32_32x32x16_bf16 v[16:31], v[148:151], v[140:143], v[16:31]
	s_waitcnt lgkmcnt(1)
	v_mfma_f32_32x32x16_bf16 v[32:47], v[156:159], v[132:135], v[32:47]
	v_mfma_f32_32x32x16_bf16 v[0:15], v[156:159], v[140:143], v[0:15]
	s_setprio 0
	ds_read_b128 v[132:135], v64 offset:36928
	ds_read_b128 v[140:143], v64 offset:41536
	ds_read_b128 v[148:151], v67 offset:64
	ds_read_b128 v[156:159], v67 offset:4672
	s_setprio 1
	v_mfma_f32_32x32x16_bf16 v[48:63], v[152:155], v[136:139], v[48:63]
	v_mfma_f32_32x32x16_bf16 v[16:31], v[152:155], v[144:147], v[16:31]
	s_waitcnt lgkmcnt(4)
	v_mfma_f32_32x32x16_bf16 v[32:47], v[160:163], v[136:139], v[32:47]
	v_mfma_f32_32x32x16_bf16 v[0:15], v[160:163], v[144:147], v[0:15]
	s_setprio 0
	ds_read_b128 v[136:139], v64 offset:36960
	ds_read_b128 v[144:147], v64 offset:41568
	ds_read_b128 v[152:155], v67 offset:96
	ds_read_b128 v[160:163], v67 offset:4704
	s_setprio 1
	s_waitcnt lgkmcnt(5)
	v_mfma_f32_32x32x16_bf16 v[48:63], v[148:151], v[132:135], v[48:63]
	v_mfma_f32_32x32x16_bf16 v[16:31], v[148:151], v[140:143], v[16:31]
	s_waitcnt lgkmcnt(4)
	v_mfma_f32_32x32x16_bf16 v[32:47], v[156:159], v[132:135], v[32:47]
	v_mfma_f32_32x32x16_bf16 v[0:15], v[156:159], v[140:143], v[0:15]
	s_setprio 0
	s_setprio 1
	s_waitcnt lgkmcnt(1)
	v_mfma_f32_32x32x16_bf16 v[48:63], v[152:155], v[136:139], v[48:63]
	v_mfma_f32_32x32x16_bf16 v[16:31], v[152:155], v[144:147], v[16:31]
	s_waitcnt lgkmcnt(0)
	v_mfma_f32_32x32x16_bf16 v[32:47], v[160:163], v[136:139], v[32:47]
	v_mfma_f32_32x32x16_bf16 v[0:15], v[160:163], v[144:147], v[0:15]
	s_setprio 0
	s_barrier
	global_load_dwordx4 v[132:135], v[74:75], off offset:896
	global_load_dwordx4 v[136:139], v[76:77], off offset:896
	global_load_dwordx4 v[140:143], v[70:71], off offset:896
	global_load_dwordx4 v[144:147], v[72:73], off offset:896
	global_load_dwordx4 v[148:151], v[78:79], off offset:896
	global_load_dwordx4 v[152:155], v[80:81], off offset:896
	s_waitcnt vmcnt(15)
	ds_write_b128 v83, v[92:95]
	ds_write_b128 v83, v[84:87] offset:9216
	ds_write_b128 v83, v[88:91] offset:18432
	s_waitcnt vmcnt(13)
	ds_write_b128 v83, v[100:103] offset:27648
	ds_write_b128 v83, v[96:99] offset:36864
	s_waitcnt vmcnt(12)
	ds_write_b128 v83, v[104:107] offset:46080
	ds_read_b128 v[84:87], v69 offset:36864
	ds_read_b128 v[88:91], v69 offset:36896
	ds_read_b128 v[92:95], v69 offset:41472
	ds_read_b128 v[96:99], v69 offset:41504
	ds_read_b128 v[100:103], v66
	ds_read_b128 v[104:107], v66 offset:32
	ds_read_b128 v[156:159], v66 offset:4608
	ds_read_b128 v[160:163], v66 offset:4640
	s_setprio 1
	s_waitcnt lgkmcnt(3)
	v_mfma_f32_32x32x16_bf16 v[48:63], v[100:103], v[84:87], v[48:63]
	v_mfma_f32_32x32x16_bf16 v[16:31], v[100:103], v[92:95], v[16:31]
	s_waitcnt lgkmcnt(1)
	v_mfma_f32_32x32x16_bf16 v[32:47], v[156:159], v[84:87], v[32:47]
	v_mfma_f32_32x32x16_bf16 v[0:15], v[156:159], v[92:95], v[0:15]
	s_setprio 0
	ds_read_b128 v[84:87], v69 offset:36928
	ds_read_b128 v[92:95], v69 offset:41536
	ds_read_b128 v[100:103], v66 offset:64
	ds_read_b128 v[156:159], v66 offset:4672
	s_setprio 1
	v_mfma_f32_32x32x16_bf16 v[48:63], v[104:107], v[88:91], v[48:63]
	v_mfma_f32_32x32x16_bf16 v[16:31], v[104:107], v[96:99], v[16:31]
	s_waitcnt lgkmcnt(4)
	v_mfma_f32_32x32x16_bf16 v[32:47], v[160:163], v[88:91], v[32:47]
	v_mfma_f32_32x32x16_bf16 v[0:15], v[160:163], v[96:99], v[0:15]
	s_setprio 0
	ds_read_b128 v[88:91], v69 offset:36960
	ds_read_b128 v[96:99], v69 offset:41568
	ds_read_b128 v[104:107], v66 offset:96
	ds_read_b128 v[160:163], v66 offset:4704
	s_setprio 1
	s_waitcnt lgkmcnt(5)
	v_mfma_f32_32x32x16_bf16 v[48:63], v[100:103], v[84:87], v[48:63]
	v_mfma_f32_32x32x16_bf16 v[16:31], v[100:103], v[92:95], v[16:31]
	s_waitcnt lgkmcnt(4)
	v_mfma_f32_32x32x16_bf16 v[32:47], v[156:159], v[84:87], v[32:47]
	v_mfma_f32_32x32x16_bf16 v[0:15], v[156:159], v[92:95], v[0:15]
	s_setprio 0
	s_setprio 1
	s_waitcnt lgkmcnt(1)
	v_mfma_f32_32x32x16_bf16 v[48:63], v[104:107], v[88:91], v[48:63]
	v_mfma_f32_32x32x16_bf16 v[16:31], v[104:107], v[96:99], v[16:31]
	s_waitcnt lgkmcnt(0)
	v_mfma_f32_32x32x16_bf16 v[32:47], v[160:163], v[88:91], v[32:47]
	v_mfma_f32_32x32x16_bf16 v[0:15], v[160:163], v[96:99], v[0:15]
	s_setprio 0
	s_barrier
	global_load_dwordx4 v[84:87], v[74:75], off offset:1024
	global_load_dwordx4 v[88:91], v[76:77], off offset:1024
	global_load_dwordx4 v[92:95], v[70:71], off offset:1024
	global_load_dwordx4 v[96:99], v[72:73], off offset:1024
	global_load_dwordx4 v[100:103], v[78:79], off offset:1024
	global_load_dwordx4 v[104:107], v[80:81], off offset:1024
	s_waitcnt vmcnt(15)
	ds_write_b128 v68, v[116:119]
	ds_write_b128 v68, v[108:111] offset:9216
	ds_write_b128 v68, v[112:115] offset:18432
	s_waitcnt vmcnt(13)
	ds_write_b128 v68, v[124:127] offset:27648
	ds_write_b128 v68, v[120:123] offset:36864
	s_waitcnt vmcnt(12)
	ds_write_b128 v68, v[128:131] offset:46080
	ds_read_b128 v[108:111], v64 offset:36864
	ds_read_b128 v[112:115], v64 offset:36896
	ds_read_b128 v[116:119], v64 offset:41472
	ds_read_b128 v[120:123], v64 offset:41504
	ds_read_b128 v[124:127], v67
	ds_read_b128 v[128:131], v67 offset:32
	ds_read_b128 v[156:159], v67 offset:4608
	ds_read_b128 v[160:163], v67 offset:4640
	s_setprio 1
	s_waitcnt lgkmcnt(3)
	v_mfma_f32_32x32x16_bf16 v[48:63], v[124:127], v[108:111], v[48:63]
	v_mfma_f32_32x32x16_bf16 v[16:31], v[124:127], v[116:119], v[16:31]
	s_waitcnt lgkmcnt(1)
	v_mfma_f32_32x32x16_bf16 v[32:47], v[156:159], v[108:111], v[32:47]
	v_mfma_f32_32x32x16_bf16 v[0:15], v[156:159], v[116:119], v[0:15]
	s_setprio 0
	ds_read_b128 v[108:111], v64 offset:36928
	ds_read_b128 v[116:119], v64 offset:41536
	ds_read_b128 v[124:127], v67 offset:64
	ds_read_b128 v[156:159], v67 offset:4672
	s_setprio 1
	v_mfma_f32_32x32x16_bf16 v[48:63], v[128:131], v[112:115], v[48:63]
	v_mfma_f32_32x32x16_bf16 v[16:31], v[128:131], v[120:123], v[16:31]
	s_waitcnt lgkmcnt(4)
	v_mfma_f32_32x32x16_bf16 v[32:47], v[160:163], v[112:115], v[32:47]
	v_mfma_f32_32x32x16_bf16 v[0:15], v[160:163], v[120:123], v[0:15]
	s_setprio 0
	ds_read_b128 v[112:115], v64 offset:36960
	ds_read_b128 v[120:123], v64 offset:41568
	ds_read_b128 v[128:131], v67 offset:96
	ds_read_b128 v[160:163], v67 offset:4704
	s_setprio 1
	s_waitcnt lgkmcnt(5)
	v_mfma_f32_32x32x16_bf16 v[48:63], v[124:127], v[108:111], v[48:63]
	v_mfma_f32_32x32x16_bf16 v[16:31], v[124:127], v[116:119], v[16:31]
	s_waitcnt lgkmcnt(4)
	v_mfma_f32_32x32x16_bf16 v[32:47], v[156:159], v[108:111], v[32:47]
	v_mfma_f32_32x32x16_bf16 v[0:15], v[156:159], v[116:119], v[0:15]
	s_setprio 0
	s_setprio 1
	s_waitcnt lgkmcnt(1)
	v_mfma_f32_32x32x16_bf16 v[48:63], v[128:131], v[112:115], v[48:63]
	v_mfma_f32_32x32x16_bf16 v[16:31], v[128:131], v[120:123], v[16:31]
	s_waitcnt lgkmcnt(0)
	v_mfma_f32_32x32x16_bf16 v[32:47], v[160:163], v[112:115], v[32:47]
	v_mfma_f32_32x32x16_bf16 v[0:15], v[160:163], v[120:123], v[0:15]
	s_setprio 0
	s_barrier
	global_load_dwordx4 v[108:111], v[74:75], off offset:1152
	global_load_dwordx4 v[112:115], v[76:77], off offset:1152
	global_load_dwordx4 v[116:119], v[70:71], off offset:1152
	global_load_dwordx4 v[120:123], v[72:73], off offset:1152
	global_load_dwordx4 v[124:127], v[78:79], off offset:1152
	global_load_dwordx4 v[128:131], v[80:81], off offset:1152
	s_waitcnt vmcnt(15)
	ds_write_b128 v83, v[140:143]
	ds_write_b128 v83, v[132:135] offset:9216
	ds_write_b128 v83, v[136:139] offset:18432
	s_waitcnt vmcnt(13)
	ds_write_b128 v83, v[148:151] offset:27648
	ds_write_b128 v83, v[144:147] offset:36864
	s_waitcnt vmcnt(12)
	ds_write_b128 v83, v[152:155] offset:46080
	ds_read_b128 v[132:135], v69 offset:36864
	ds_read_b128 v[136:139], v69 offset:36896
	ds_read_b128 v[140:143], v69 offset:41472
	ds_read_b128 v[144:147], v69 offset:41504
	ds_read_b128 v[148:151], v66
	ds_read_b128 v[152:155], v66 offset:32
	ds_read_b128 v[156:159], v66 offset:4608
	ds_read_b128 v[160:163], v66 offset:4640
	s_setprio 1
	s_waitcnt lgkmcnt(3)
	v_mfma_f32_32x32x16_bf16 v[48:63], v[148:151], v[132:135], v[48:63]
	v_mfma_f32_32x32x16_bf16 v[16:31], v[148:151], v[140:143], v[16:31]
	s_waitcnt lgkmcnt(1)
	v_mfma_f32_32x32x16_bf16 v[32:47], v[156:159], v[132:135], v[32:47]
	v_mfma_f32_32x32x16_bf16 v[0:15], v[156:159], v[140:143], v[0:15]
	s_setprio 0
	ds_read_b128 v[132:135], v69 offset:36928
	ds_read_b128 v[140:143], v69 offset:41536
	ds_read_b128 v[148:151], v66 offset:64
	ds_read_b128 v[156:159], v66 offset:4672
	s_setprio 1
	v_mfma_f32_32x32x16_bf16 v[48:63], v[152:155], v[136:139], v[48:63]
	v_mfma_f32_32x32x16_bf16 v[16:31], v[152:155], v[144:147], v[16:31]
	s_waitcnt lgkmcnt(4)
	v_mfma_f32_32x32x16_bf16 v[32:47], v[160:163], v[136:139], v[32:47]
	v_mfma_f32_32x32x16_bf16 v[0:15], v[160:163], v[144:147], v[0:15]
	s_setprio 0
	ds_read_b128 v[136:139], v69 offset:36960
	ds_read_b128 v[144:147], v69 offset:41568
	ds_read_b128 v[152:155], v66 offset:96
	ds_read_b128 v[160:163], v66 offset:4704
	s_setprio 1
	s_waitcnt lgkmcnt(5)
	v_mfma_f32_32x32x16_bf16 v[48:63], v[148:151], v[132:135], v[48:63]
	v_mfma_f32_32x32x16_bf16 v[16:31], v[148:151], v[140:143], v[16:31]
	s_waitcnt lgkmcnt(4)
	v_mfma_f32_32x32x16_bf16 v[32:47], v[156:159], v[132:135], v[32:47]
	v_mfma_f32_32x32x16_bf16 v[0:15], v[156:159], v[140:143], v[0:15]
	s_setprio 0
	s_setprio 1
	s_waitcnt lgkmcnt(1)
	v_mfma_f32_32x32x16_bf16 v[48:63], v[152:155], v[136:139], v[48:63]
	v_mfma_f32_32x32x16_bf16 v[16:31], v[152:155], v[144:147], v[16:31]
	s_waitcnt lgkmcnt(0)
	v_mfma_f32_32x32x16_bf16 v[32:47], v[160:163], v[136:139], v[32:47]
	v_mfma_f32_32x32x16_bf16 v[0:15], v[160:163], v[144:147], v[0:15]
	s_setprio 0
	s_barrier
	global_load_dwordx4 v[132:135], v[74:75], off offset:1280
	global_load_dwordx4 v[136:139], v[76:77], off offset:1280
	global_load_dwordx4 v[140:143], v[70:71], off offset:1280
	global_load_dwordx4 v[144:147], v[72:73], off offset:1280
	global_load_dwordx4 v[148:151], v[78:79], off offset:1280
	global_load_dwordx4 v[152:155], v[80:81], off offset:1280
	s_waitcnt vmcnt(15)
	ds_write_b128 v68, v[92:95]
	ds_write_b128 v68, v[84:87] offset:9216
	ds_write_b128 v68, v[88:91] offset:18432
	s_waitcnt vmcnt(13)
	ds_write_b128 v68, v[100:103] offset:27648
	ds_write_b128 v68, v[96:99] offset:36864
	s_waitcnt vmcnt(12)
	ds_write_b128 v68, v[104:107] offset:46080
	ds_read_b128 v[84:87], v64 offset:36864
	ds_read_b128 v[88:91], v64 offset:36896
	ds_read_b128 v[92:95], v64 offset:41472
	ds_read_b128 v[96:99], v64 offset:41504
	ds_read_b128 v[100:103], v67
	ds_read_b128 v[104:107], v67 offset:32
	ds_read_b128 v[156:159], v67 offset:4608
	ds_read_b128 v[160:163], v67 offset:4640
	s_setprio 1
	s_waitcnt lgkmcnt(3)
	v_mfma_f32_32x32x16_bf16 v[48:63], v[100:103], v[84:87], v[48:63]
	v_mfma_f32_32x32x16_bf16 v[16:31], v[100:103], v[92:95], v[16:31]
	s_waitcnt lgkmcnt(1)
	v_mfma_f32_32x32x16_bf16 v[32:47], v[156:159], v[84:87], v[32:47]
	v_mfma_f32_32x32x16_bf16 v[0:15], v[156:159], v[92:95], v[0:15]
	s_setprio 0
	ds_read_b128 v[84:87], v64 offset:36928
	ds_read_b128 v[92:95], v64 offset:41536
	ds_read_b128 v[100:103], v67 offset:64
	ds_read_b128 v[156:159], v67 offset:4672
	s_setprio 1
	v_mfma_f32_32x32x16_bf16 v[48:63], v[104:107], v[88:91], v[48:63]
	v_mfma_f32_32x32x16_bf16 v[16:31], v[104:107], v[96:99], v[16:31]
	s_waitcnt lgkmcnt(4)
	v_mfma_f32_32x32x16_bf16 v[32:47], v[160:163], v[88:91], v[32:47]
	v_mfma_f32_32x32x16_bf16 v[0:15], v[160:163], v[96:99], v[0:15]
	s_setprio 0
	ds_read_b128 v[88:91], v64 offset:36960
	ds_read_b128 v[96:99], v64 offset:41568
	ds_read_b128 v[104:107], v67 offset:96
	ds_read_b128 v[160:163], v67 offset:4704
	s_setprio 1
	s_waitcnt lgkmcnt(5)
	v_mfma_f32_32x32x16_bf16 v[48:63], v[100:103], v[84:87], v[48:63]
	v_mfma_f32_32x32x16_bf16 v[16:31], v[100:103], v[92:95], v[16:31]
	s_waitcnt lgkmcnt(4)
	v_mfma_f32_32x32x16_bf16 v[32:47], v[156:159], v[84:87], v[32:47]
	v_mfma_f32_32x32x16_bf16 v[0:15], v[156:159], v[92:95], v[0:15]
	s_setprio 0
	s_setprio 1
	s_waitcnt lgkmcnt(1)
	v_mfma_f32_32x32x16_bf16 v[48:63], v[104:107], v[88:91], v[48:63]
	v_mfma_f32_32x32x16_bf16 v[16:31], v[104:107], v[96:99], v[16:31]
	s_waitcnt lgkmcnt(0)
	v_mfma_f32_32x32x16_bf16 v[32:47], v[160:163], v[88:91], v[32:47]
	v_mfma_f32_32x32x16_bf16 v[0:15], v[160:163], v[96:99], v[0:15]
	s_setprio 0
	s_barrier
	global_load_dwordx4 v[84:87], v[74:75], off offset:1408
	global_load_dwordx4 v[88:91], v[76:77], off offset:1408
	global_load_dwordx4 v[92:95], v[70:71], off offset:1408
	global_load_dwordx4 v[96:99], v[72:73], off offset:1408
	global_load_dwordx4 v[100:103], v[78:79], off offset:1408
	global_load_dwordx4 v[104:107], v[80:81], off offset:1408
	s_waitcnt vmcnt(15)
	ds_write_b128 v83, v[116:119]
	ds_write_b128 v83, v[108:111] offset:9216
	ds_write_b128 v83, v[112:115] offset:18432
	s_waitcnt vmcnt(13)
	ds_write_b128 v83, v[124:127] offset:27648
	ds_write_b128 v83, v[120:123] offset:36864
	s_waitcnt vmcnt(12)
	ds_write_b128 v83, v[128:131] offset:46080
	ds_read_b128 v[108:111], v69 offset:36864
	ds_read_b128 v[112:115], v69 offset:36896
	ds_read_b128 v[116:119], v69 offset:41472
	ds_read_b128 v[120:123], v69 offset:41504
	ds_read_b128 v[124:127], v66
	ds_read_b128 v[128:131], v66 offset:32
	ds_read_b128 v[156:159], v66 offset:4608
	ds_read_b128 v[160:163], v66 offset:4640
	s_setprio 1
	s_waitcnt lgkmcnt(3)
	v_mfma_f32_32x32x16_bf16 v[48:63], v[124:127], v[108:111], v[48:63]
	v_mfma_f32_32x32x16_bf16 v[16:31], v[124:127], v[116:119], v[16:31]
	s_waitcnt lgkmcnt(1)
	v_mfma_f32_32x32x16_bf16 v[32:47], v[156:159], v[108:111], v[32:47]
	v_mfma_f32_32x32x16_bf16 v[0:15], v[156:159], v[116:119], v[0:15]
	s_setprio 0
	ds_read_b128 v[108:111], v69 offset:36928
	ds_read_b128 v[116:119], v69 offset:41536
	ds_read_b128 v[124:127], v66 offset:64
	ds_read_b128 v[156:159], v66 offset:4672
	s_setprio 1
	v_mfma_f32_32x32x16_bf16 v[48:63], v[128:131], v[112:115], v[48:63]
	v_mfma_f32_32x32x16_bf16 v[16:31], v[128:131], v[120:123], v[16:31]
	s_waitcnt lgkmcnt(4)
	v_mfma_f32_32x32x16_bf16 v[32:47], v[160:163], v[112:115], v[32:47]
	v_mfma_f32_32x32x16_bf16 v[0:15], v[160:163], v[120:123], v[0:15]
	s_setprio 0
	ds_read_b128 v[112:115], v69 offset:36960
	ds_read_b128 v[120:123], v69 offset:41568
	ds_read_b128 v[128:131], v66 offset:96
	ds_read_b128 v[160:163], v66 offset:4704
	s_setprio 1
	s_waitcnt lgkmcnt(5)
	v_mfma_f32_32x32x16_bf16 v[48:63], v[124:127], v[108:111], v[48:63]
	v_mfma_f32_32x32x16_bf16 v[16:31], v[124:127], v[116:119], v[16:31]
	s_waitcnt lgkmcnt(4)
	v_mfma_f32_32x32x16_bf16 v[32:47], v[156:159], v[108:111], v[32:47]
	v_mfma_f32_32x32x16_bf16 v[0:15], v[156:159], v[116:119], v[0:15]
	s_setprio 0
	s_setprio 1
	s_waitcnt lgkmcnt(1)
	v_mfma_f32_32x32x16_bf16 v[48:63], v[128:131], v[112:115], v[48:63]
	v_mfma_f32_32x32x16_bf16 v[16:31], v[128:131], v[120:123], v[16:31]
	s_waitcnt lgkmcnt(0)
	v_mfma_f32_32x32x16_bf16 v[32:47], v[160:163], v[112:115], v[32:47]
	v_mfma_f32_32x32x16_bf16 v[0:15], v[160:163], v[120:123], v[0:15]
	s_setprio 0
	s_barrier
	global_load_dwordx4 v[108:111], v[74:75], off offset:1536
	global_load_dwordx4 v[112:115], v[76:77], off offset:1536
	global_load_dwordx4 v[116:119], v[70:71], off offset:1536
	global_load_dwordx4 v[120:123], v[72:73], off offset:1536
	global_load_dwordx4 v[124:127], v[78:79], off offset:1536
	global_load_dwordx4 v[128:131], v[80:81], off offset:1536
	s_waitcnt vmcnt(15)
	ds_write_b128 v68, v[140:143]
	ds_write_b128 v68, v[132:135] offset:9216
	ds_write_b128 v68, v[136:139] offset:18432
	s_waitcnt vmcnt(13)
	ds_write_b128 v68, v[148:151] offset:27648
	ds_write_b128 v68, v[144:147] offset:36864
	s_waitcnt vmcnt(12)
	ds_write_b128 v68, v[152:155] offset:46080
	ds_read_b128 v[132:135], v64 offset:36864
	ds_read_b128 v[136:139], v64 offset:36896
	ds_read_b128 v[140:143], v64 offset:41472
	ds_read_b128 v[144:147], v64 offset:41504
	ds_read_b128 v[148:151], v67
	ds_read_b128 v[152:155], v67 offset:32
	ds_read_b128 v[156:159], v67 offset:4608
	ds_read_b128 v[160:163], v67 offset:4640
	s_setprio 1
	s_waitcnt lgkmcnt(3)
	v_mfma_f32_32x32x16_bf16 v[48:63], v[148:151], v[132:135], v[48:63]
	v_mfma_f32_32x32x16_bf16 v[16:31], v[148:151], v[140:143], v[16:31]
	s_waitcnt lgkmcnt(1)
	v_mfma_f32_32x32x16_bf16 v[32:47], v[156:159], v[132:135], v[32:47]
	v_mfma_f32_32x32x16_bf16 v[0:15], v[156:159], v[140:143], v[0:15]
	s_setprio 0
	ds_read_b128 v[132:135], v64 offset:36928
	ds_read_b128 v[140:143], v64 offset:41536
	ds_read_b128 v[148:151], v67 offset:64
	ds_read_b128 v[156:159], v67 offset:4672
	s_setprio 1
	v_mfma_f32_32x32x16_bf16 v[48:63], v[152:155], v[136:139], v[48:63]
	v_mfma_f32_32x32x16_bf16 v[16:31], v[152:155], v[144:147], v[16:31]
	s_waitcnt lgkmcnt(4)
	v_mfma_f32_32x32x16_bf16 v[32:47], v[160:163], v[136:139], v[32:47]
	v_mfma_f32_32x32x16_bf16 v[0:15], v[160:163], v[144:147], v[0:15]
	s_setprio 0
	ds_read_b128 v[136:139], v64 offset:36960
	ds_read_b128 v[144:147], v64 offset:41568
	ds_read_b128 v[152:155], v67 offset:96
	ds_read_b128 v[160:163], v67 offset:4704
	s_setprio 1
	s_waitcnt lgkmcnt(5)
	v_mfma_f32_32x32x16_bf16 v[48:63], v[148:151], v[132:135], v[48:63]
	v_mfma_f32_32x32x16_bf16 v[16:31], v[148:151], v[140:143], v[16:31]
	s_waitcnt lgkmcnt(4)
	v_mfma_f32_32x32x16_bf16 v[32:47], v[156:159], v[132:135], v[32:47]
	v_mfma_f32_32x32x16_bf16 v[0:15], v[156:159], v[140:143], v[0:15]
	s_setprio 0
	s_setprio 1
	s_waitcnt lgkmcnt(1)
	v_mfma_f32_32x32x16_bf16 v[48:63], v[152:155], v[136:139], v[48:63]
	v_mfma_f32_32x32x16_bf16 v[16:31], v[152:155], v[144:147], v[16:31]
	s_waitcnt lgkmcnt(0)
	v_mfma_f32_32x32x16_bf16 v[32:47], v[160:163], v[136:139], v[32:47]
	v_mfma_f32_32x32x16_bf16 v[0:15], v[160:163], v[144:147], v[0:15]
	s_setprio 0
	s_barrier
	global_load_dwordx4 v[132:135], v[74:75], off offset:1664
	global_load_dwordx4 v[136:139], v[76:77], off offset:1664
	global_load_dwordx4 v[140:143], v[70:71], off offset:1664
	global_load_dwordx4 v[144:147], v[72:73], off offset:1664
	global_load_dwordx4 v[148:151], v[78:79], off offset:1664
	global_load_dwordx4 v[152:155], v[80:81], off offset:1664
	s_waitcnt vmcnt(15)
	ds_write_b128 v83, v[92:95]
	ds_write_b128 v83, v[84:87] offset:9216
	ds_write_b128 v83, v[88:91] offset:18432
	s_waitcnt vmcnt(13)
	ds_write_b128 v83, v[100:103] offset:27648
	ds_write_b128 v83, v[96:99] offset:36864
	s_waitcnt vmcnt(12)
	ds_write_b128 v83, v[104:107] offset:46080
	ds_read_b128 v[84:87], v69 offset:36864
	ds_read_b128 v[88:91], v69 offset:36896
	ds_read_b128 v[92:95], v69 offset:41472
	ds_read_b128 v[96:99], v69 offset:41504
	ds_read_b128 v[100:103], v66
	ds_read_b128 v[104:107], v66 offset:32
	ds_read_b128 v[156:159], v66 offset:4608
	ds_read_b128 v[160:163], v66 offset:4640
	s_setprio 1
	s_waitcnt lgkmcnt(3)
	v_mfma_f32_32x32x16_bf16 v[48:63], v[100:103], v[84:87], v[48:63]
	v_mfma_f32_32x32x16_bf16 v[16:31], v[100:103], v[92:95], v[16:31]
	s_waitcnt lgkmcnt(1)
	v_mfma_f32_32x32x16_bf16 v[32:47], v[156:159], v[84:87], v[32:47]
	v_mfma_f32_32x32x16_bf16 v[0:15], v[156:159], v[92:95], v[0:15]
	s_setprio 0
	ds_read_b128 v[84:87], v69 offset:36928
	ds_read_b128 v[92:95], v69 offset:41536
	ds_read_b128 v[100:103], v66 offset:64
	ds_read_b128 v[156:159], v66 offset:4672
	s_setprio 1
	v_mfma_f32_32x32x16_bf16 v[48:63], v[104:107], v[88:91], v[48:63]
	v_mfma_f32_32x32x16_bf16 v[16:31], v[104:107], v[96:99], v[16:31]
	s_waitcnt lgkmcnt(4)
	v_mfma_f32_32x32x16_bf16 v[32:47], v[160:163], v[88:91], v[32:47]
	v_mfma_f32_32x32x16_bf16 v[0:15], v[160:163], v[96:99], v[0:15]
	s_setprio 0
	ds_read_b128 v[88:91], v69 offset:36960
	ds_read_b128 v[96:99], v69 offset:41568
	ds_read_b128 v[104:107], v66 offset:96
	ds_read_b128 v[160:163], v66 offset:4704
	s_setprio 1
	s_waitcnt lgkmcnt(5)
	v_mfma_f32_32x32x16_bf16 v[48:63], v[100:103], v[84:87], v[48:63]
	v_mfma_f32_32x32x16_bf16 v[16:31], v[100:103], v[92:95], v[16:31]
	s_waitcnt lgkmcnt(4)
	v_mfma_f32_32x32x16_bf16 v[32:47], v[156:159], v[84:87], v[32:47]
	v_mfma_f32_32x32x16_bf16 v[0:15], v[156:159], v[92:95], v[0:15]
	s_setprio 0
	s_setprio 1
	s_waitcnt lgkmcnt(1)
	v_mfma_f32_32x32x16_bf16 v[48:63], v[104:107], v[88:91], v[48:63]
	v_mfma_f32_32x32x16_bf16 v[16:31], v[104:107], v[96:99], v[16:31]
	s_waitcnt lgkmcnt(0)
	v_mfma_f32_32x32x16_bf16 v[32:47], v[160:163], v[88:91], v[32:47]
	v_mfma_f32_32x32x16_bf16 v[0:15], v[160:163], v[96:99], v[0:15]
	s_setprio 0
	s_barrier
	global_load_dwordx4 v[84:87], v[74:75], off offset:1792
	global_load_dwordx4 v[88:91], v[76:77], off offset:1792
	global_load_dwordx4 v[92:95], v[70:71], off offset:1792
	global_load_dwordx4 v[96:99], v[72:73], off offset:1792
	global_load_dwordx4 v[100:103], v[78:79], off offset:1792
	global_load_dwordx4 v[104:107], v[80:81], off offset:1792
	s_waitcnt vmcnt(15)
	ds_write_b128 v68, v[116:119]
	ds_write_b128 v68, v[108:111] offset:9216
	ds_write_b128 v68, v[112:115] offset:18432
	s_waitcnt vmcnt(13)
	ds_write_b128 v68, v[124:127] offset:27648
	ds_write_b128 v68, v[120:123] offset:36864
	s_waitcnt vmcnt(12)
	ds_write_b128 v68, v[128:131] offset:46080
	ds_read_b128 v[108:111], v64 offset:36864
	ds_read_b128 v[112:115], v64 offset:36896
	ds_read_b128 v[116:119], v64 offset:41472
	ds_read_b128 v[120:123], v64 offset:41504
	ds_read_b128 v[124:127], v67
	ds_read_b128 v[128:131], v67 offset:32
	ds_read_b128 v[156:159], v67 offset:4608
	ds_read_b128 v[160:163], v67 offset:4640
	s_setprio 1
	s_waitcnt lgkmcnt(3)
	v_mfma_f32_32x32x16_bf16 v[48:63], v[124:127], v[108:111], v[48:63]
	v_mfma_f32_32x32x16_bf16 v[16:31], v[124:127], v[116:119], v[16:31]
	s_waitcnt lgkmcnt(1)
	v_mfma_f32_32x32x16_bf16 v[32:47], v[156:159], v[108:111], v[32:47]
	v_mfma_f32_32x32x16_bf16 v[0:15], v[156:159], v[116:119], v[0:15]
	s_setprio 0
	ds_read_b128 v[108:111], v64 offset:36928
	ds_read_b128 v[116:119], v64 offset:41536
	ds_read_b128 v[124:127], v67 offset:64
	ds_read_b128 v[156:159], v67 offset:4672
	s_setprio 1
	v_mfma_f32_32x32x16_bf16 v[48:63], v[128:131], v[112:115], v[48:63]
	v_mfma_f32_32x32x16_bf16 v[16:31], v[128:131], v[120:123], v[16:31]
	s_waitcnt lgkmcnt(4)
	v_mfma_f32_32x32x16_bf16 v[32:47], v[160:163], v[112:115], v[32:47]
	v_mfma_f32_32x32x16_bf16 v[0:15], v[160:163], v[120:123], v[0:15]
	s_setprio 0
	ds_read_b128 v[112:115], v64 offset:36960
	ds_read_b128 v[120:123], v64 offset:41568
	ds_read_b128 v[128:131], v67 offset:96
	ds_read_b128 v[160:163], v67 offset:4704
	s_setprio 1
	s_waitcnt lgkmcnt(5)
	v_mfma_f32_32x32x16_bf16 v[48:63], v[124:127], v[108:111], v[48:63]
	v_mfma_f32_32x32x16_bf16 v[16:31], v[124:127], v[116:119], v[16:31]
	s_waitcnt lgkmcnt(4)
	v_mfma_f32_32x32x16_bf16 v[32:47], v[156:159], v[108:111], v[32:47]
	v_mfma_f32_32x32x16_bf16 v[0:15], v[156:159], v[116:119], v[0:15]
	s_setprio 0
	s_setprio 1
	s_waitcnt lgkmcnt(1)
	v_mfma_f32_32x32x16_bf16 v[48:63], v[128:131], v[112:115], v[48:63]
	v_mfma_f32_32x32x16_bf16 v[16:31], v[128:131], v[120:123], v[16:31]
	s_waitcnt lgkmcnt(0)
	v_mfma_f32_32x32x16_bf16 v[32:47], v[160:163], v[112:115], v[32:47]
	v_mfma_f32_32x32x16_bf16 v[0:15], v[160:163], v[120:123], v[0:15]
	s_setprio 0
	s_barrier
	global_load_dwordx4 v[108:111], v[74:75], off offset:1920
	s_nop 0
	global_load_dwordx4 v[74:77], v[76:77], off offset:1920
	s_nop 0
	global_load_dwordx4 v[112:115], v[70:71], off offset:1920
	s_nop 0
	global_load_dwordx4 v[70:73], v[72:73], off offset:1920
	s_nop 0
	global_load_dwordx4 v[116:119], v[78:79], off offset:1920
	s_nop 0
	global_load_dwordx4 v[78:81], v[80:81], off offset:1920
	s_waitcnt vmcnt(15)
	ds_write_b128 v83, v[140:143]
	ds_write_b128 v83, v[132:135] offset:9216
	ds_write_b128 v83, v[136:139] offset:18432
	s_waitcnt vmcnt(13)
	ds_write_b128 v83, v[148:151] offset:27648
	ds_write_b128 v83, v[144:147] offset:36864
	s_waitcnt vmcnt(12)
	ds_write_b128 v83, v[152:155] offset:46080
	ds_read_b128 v[120:123], v69 offset:36864
	ds_read_b128 v[124:127], v69 offset:36896
	ds_read_b128 v[128:131], v69 offset:41472
	ds_read_b128 v[132:135], v69 offset:41504
	ds_read_b128 v[136:139], v66
	ds_read_b128 v[140:143], v66 offset:32
	ds_read_b128 v[144:147], v66 offset:4608
	ds_read_b128 v[148:151], v66 offset:4640
	s_setprio 1
	s_waitcnt lgkmcnt(3)
	v_mfma_f32_32x32x16_bf16 v[48:63], v[136:139], v[120:123], v[48:63]
	v_mfma_f32_32x32x16_bf16 v[16:31], v[136:139], v[128:131], v[16:31]
	s_waitcnt lgkmcnt(1)
	v_mfma_f32_32x32x16_bf16 v[32:47], v[144:147], v[120:123], v[32:47]
	v_mfma_f32_32x32x16_bf16 v[0:15], v[144:147], v[128:131], v[0:15]
	s_setprio 0
	ds_read_b128 v[120:123], v69 offset:36928
	ds_read_b128 v[128:131], v69 offset:41536
	ds_read_b128 v[136:139], v66 offset:64
	ds_read_b128 v[144:147], v66 offset:4672
	s_setprio 1
	v_mfma_f32_32x32x16_bf16 v[48:63], v[140:143], v[124:127], v[48:63]
	v_mfma_f32_32x32x16_bf16 v[16:31], v[140:143], v[132:135], v[16:31]
	s_waitcnt lgkmcnt(4)
	v_mfma_f32_32x32x16_bf16 v[32:47], v[148:151], v[124:127], v[32:47]
	v_mfma_f32_32x32x16_bf16 v[0:15], v[148:151], v[132:135], v[0:15]
	s_setprio 0
	ds_read_b128 v[124:127], v69 offset:36960
	ds_read_b128 v[132:135], v69 offset:41568
	ds_read_b128 v[140:143], v66 offset:96
	ds_read_b128 v[148:151], v66 offset:4704
	s_setprio 1
	s_waitcnt lgkmcnt(5)
	v_mfma_f32_32x32x16_bf16 v[48:63], v[136:139], v[120:123], v[48:63]
	v_mfma_f32_32x32x16_bf16 v[16:31], v[136:139], v[128:131], v[16:31]
	s_waitcnt lgkmcnt(4)
	v_mfma_f32_32x32x16_bf16 v[32:47], v[144:147], v[120:123], v[32:47]
	v_mfma_f32_32x32x16_bf16 v[0:15], v[144:147], v[128:131], v[0:15]
	s_setprio 0
	s_setprio 1
	s_waitcnt lgkmcnt(1)
	v_mfma_f32_32x32x16_bf16 v[48:63], v[140:143], v[124:127], v[48:63]
	v_mfma_f32_32x32x16_bf16 v[16:31], v[140:143], v[132:135], v[16:31]
	s_waitcnt lgkmcnt(0)
	v_mfma_f32_32x32x16_bf16 v[32:47], v[148:151], v[124:127], v[32:47]
	v_mfma_f32_32x32x16_bf16 v[0:15], v[148:151], v[132:135], v[0:15]
	s_setprio 0
	s_barrier
	s_waitcnt vmcnt(9)
	ds_write_b128 v68, v[92:95]
	ds_write_b128 v68, v[84:87] offset:9216
	ds_write_b128 v68, v[88:91] offset:18432
	s_waitcnt vmcnt(7)
	ds_write_b128 v68, v[100:103] offset:27648
	ds_write_b128 v68, v[96:99] offset:36864
	s_waitcnt vmcnt(6)
	ds_write_b128 v68, v[104:107] offset:46080
	ds_read_b128 v[84:87], v64 offset:36864
	ds_read_b128 v[88:91], v64 offset:36896
	ds_read_b128 v[92:95], v64 offset:41472
	ds_read_b128 v[96:99], v64 offset:41504
	ds_read_b128 v[100:103], v67
	ds_read_b128 v[104:107], v67 offset:32
	ds_read_b128 v[120:123], v67 offset:4608
	ds_read_b128 v[124:127], v67 offset:4640
	s_setprio 1
	s_waitcnt lgkmcnt(3)
	v_mfma_f32_32x32x16_bf16 v[48:63], v[100:103], v[84:87], v[48:63]
	v_mfma_f32_32x32x16_bf16 v[16:31], v[100:103], v[92:95], v[16:31]
	s_waitcnt lgkmcnt(1)
	v_mfma_f32_32x32x16_bf16 v[32:47], v[120:123], v[84:87], v[32:47]
	v_mfma_f32_32x32x16_bf16 v[0:15], v[120:123], v[92:95], v[0:15]
	s_setprio 0
	ds_read_b128 v[84:87], v64 offset:36928
	ds_read_b128 v[92:95], v64 offset:41536
	ds_read_b128 v[100:103], v67 offset:64
	ds_read_b128 v[120:123], v67 offset:4672
	s_setprio 1
	v_mfma_f32_32x32x16_bf16 v[48:63], v[104:107], v[88:91], v[48:63]
	v_mfma_f32_32x32x16_bf16 v[16:31], v[104:107], v[96:99], v[16:31]
	s_waitcnt lgkmcnt(4)
	v_mfma_f32_32x32x16_bf16 v[32:47], v[124:127], v[88:91], v[32:47]
	v_mfma_f32_32x32x16_bf16 v[0:15], v[124:127], v[96:99], v[0:15]
	s_setprio 0
	ds_read_b128 v[88:91], v64 offset:36960
	ds_read_b128 v[96:99], v64 offset:41568
	ds_read_b128 v[104:107], v67 offset:96
	ds_read_b128 v[124:127], v67 offset:4704
	s_setprio 1
	s_waitcnt lgkmcnt(5)
	v_mfma_f32_32x32x16_bf16 v[48:63], v[100:103], v[84:87], v[48:63]
	v_mfma_f32_32x32x16_bf16 v[16:31], v[100:103], v[92:95], v[16:31]
	s_waitcnt lgkmcnt(4)
	v_mfma_f32_32x32x16_bf16 v[32:47], v[120:123], v[84:87], v[32:47]
	v_mfma_f32_32x32x16_bf16 v[0:15], v[120:123], v[92:95], v[0:15]
	s_setprio 0
	s_setprio 1
	s_waitcnt lgkmcnt(1)
	v_mfma_f32_32x32x16_bf16 v[48:63], v[104:107], v[88:91], v[48:63]
	v_mfma_f32_32x32x16_bf16 v[16:31], v[104:107], v[96:99], v[16:31]
	s_waitcnt lgkmcnt(0)
	v_mfma_f32_32x32x16_bf16 v[32:47], v[124:127], v[88:91], v[32:47]
	v_mfma_f32_32x32x16_bf16 v[0:15], v[124:127], v[96:99], v[0:15]
	s_setprio 0
	s_barrier
	s_waitcnt vmcnt(3)
	ds_write_b128 v83, v[112:115]
	ds_write_b128 v83, v[108:111] offset:9216
	ds_write_b128 v83, v[74:77] offset:18432
	s_waitcnt vmcnt(1)
	ds_write_b128 v83, v[116:119] offset:27648
	ds_write_b128 v83, v[70:73] offset:36864
	s_waitcnt vmcnt(0)
	ds_write_b128 v83, v[78:81] offset:46080
	ds_read_b128 v[70:73], v69 offset:36864
	ds_read_b128 v[74:77], v69 offset:36896
	ds_read_b128 v[78:81], v69 offset:41472
	ds_read_b128 v[84:87], v69 offset:41504
	ds_read_b128 v[88:91], v66
	ds_read_b128 v[92:95], v66 offset:32
	ds_read_b128 v[96:99], v66 offset:4608
	ds_read_b128 v[100:103], v66 offset:4640
	s_setprio 1
	s_waitcnt lgkmcnt(3)
	v_mfma_f32_32x32x16_bf16 v[48:63], v[88:91], v[70:73], v[48:63]
	v_mfma_f32_32x32x16_bf16 v[16:31], v[88:91], v[78:81], v[16:31]
	s_waitcnt lgkmcnt(1)
	v_mfma_f32_32x32x16_bf16 v[32:47], v[96:99], v[70:73], v[32:47]
	v_mfma_f32_32x32x16_bf16 v[0:15], v[96:99], v[78:81], v[0:15]
	s_setprio 0
	ds_read_b128 v[70:73], v69 offset:36928
	ds_read_b128 v[78:81], v69 offset:41536
	ds_read_b128 v[88:91], v66 offset:64
	ds_read_b128 v[96:99], v66 offset:4672
	s_setprio 1
	v_mfma_f32_32x32x16_bf16 v[48:63], v[92:95], v[74:77], v[48:63]
	v_mfma_f32_32x32x16_bf16 v[16:31], v[92:95], v[84:87], v[16:31]
	s_waitcnt lgkmcnt(4)
	v_mfma_f32_32x32x16_bf16 v[32:47], v[100:103], v[74:77], v[32:47]
	v_mfma_f32_32x32x16_bf16 v[0:15], v[100:103], v[84:87], v[0:15]
	s_setprio 0
	ds_read_b128 v[74:77], v69 offset:36960
	ds_read_b128 v[84:87], v69 offset:41568
	ds_read_b128 v[92:95], v66 offset:96
	ds_read_b128 v[100:103], v66 offset:4704
	s_setprio 1
	s_waitcnt lgkmcnt(5)
	v_mfma_f32_32x32x16_bf16 v[48:63], v[88:91], v[70:73], v[48:63]
	v_mfma_f32_32x32x16_bf16 v[16:31], v[88:91], v[78:81], v[16:31]
	s_waitcnt lgkmcnt(4)
	v_mfma_f32_32x32x16_bf16 v[32:47], v[96:99], v[70:73], v[32:47]
	v_mfma_f32_32x32x16_bf16 v[0:15], v[96:99], v[78:81], v[0:15]
	s_setprio 0
	s_setprio 1
	s_waitcnt lgkmcnt(1)
	v_mfma_f32_32x32x16_bf16 v[48:63], v[92:95], v[74:77], v[48:63]
	v_mfma_f32_32x32x16_bf16 v[16:31], v[92:95], v[84:87], v[16:31]
	s_waitcnt lgkmcnt(0)
	v_mfma_f32_32x32x16_bf16 v[32:47], v[100:103], v[74:77], v[32:47]
	v_mfma_f32_32x32x16_bf16 v[0:15], v[100:103], v[84:87], v[0:15]
	s_setprio 0
	s_barrier
	ds_read_b128 v[68:71], v64 offset:36864
	ds_read_b128 v[72:75], v64 offset:36896
	ds_read_b128 v[76:79], v64 offset:41472
	ds_read_b128 v[84:87], v64 offset:41504
	ds_read_b128 v[88:91], v67
	ds_read_b128 v[92:95], v67 offset:32
	ds_read_b128 v[96:99], v67 offset:4608
	ds_read_b128 v[100:103], v67 offset:4640
	s_setprio 1
	s_waitcnt lgkmcnt(3)
	v_mfma_f32_32x32x16_bf16 v[48:63], v[88:91], v[68:71], v[48:63]
	v_mfma_f32_32x32x16_bf16 v[16:31], v[88:91], v[76:79], v[16:31]
	s_waitcnt lgkmcnt(1)
	v_mfma_f32_32x32x16_bf16 v[32:47], v[96:99], v[68:71], v[32:47]
	v_mfma_f32_32x32x16_bf16 v[0:15], v[96:99], v[76:79], v[0:15]
	s_setprio 0
	ds_read_b128 v[68:71], v64 offset:36928
	ds_read_b128 v[76:79], v64 offset:41536
	ds_read_b128 v[88:91], v67 offset:64
	ds_read_b128 v[96:99], v67 offset:4672
	s_setprio 1
	v_mfma_f32_32x32x16_bf16 v[48:63], v[92:95], v[72:75], v[48:63]
	v_mfma_f32_32x32x16_bf16 v[16:31], v[92:95], v[84:87], v[16:31]
	s_waitcnt lgkmcnt(4)
	v_mfma_f32_32x32x16_bf16 v[32:47], v[100:103], v[72:75], v[32:47]
	v_mfma_f32_32x32x16_bf16 v[0:15], v[100:103], v[84:87], v[0:15]
	s_setprio 0
	ds_read_b128 v[72:75], v64 offset:36960
	ds_read_b128 v[84:87], v64 offset:41568
	ds_read_b128 v[92:95], v67 offset:96
	ds_read_b128 v[100:103], v67 offset:4704
	s_setprio 1
	s_waitcnt lgkmcnt(5)
	v_mfma_f32_32x32x16_bf16 v[48:63], v[88:91], v[68:71], v[48:63]
	v_mfma_f32_32x32x16_bf16 v[16:31], v[88:91], v[76:79], v[16:31]
	s_waitcnt lgkmcnt(4)
	v_mfma_f32_32x32x16_bf16 v[32:47], v[96:99], v[68:71], v[32:47]
	v_mfma_f32_32x32x16_bf16 v[0:15], v[96:99], v[76:79], v[0:15]
	s_setprio 0
	s_setprio 1
	s_waitcnt lgkmcnt(1)
	v_mfma_f32_32x32x16_bf16 v[48:63], v[92:95], v[72:75], v[48:63]
	v_mfma_f32_32x32x16_bf16 v[16:31], v[92:95], v[84:87], v[16:31]
	s_waitcnt lgkmcnt(0)
	v_mfma_f32_32x32x16_bf16 v[32:47], v[100:103], v[72:75], v[32:47]
	v_mfma_f32_32x32x16_bf16 v[0:15], v[100:103], v[84:87], v[0:15]
	s_setprio 0
	s_add_i32 s5, s4, 0xffffe000
	s_lshr_b32 s5, s5, 12
	s_add_i32 s5, s5, 6
	s_cmp_gt_i32 s27, 63
	s_cselect_b32 s5, s5, 5
	v_lshrrev_b32_e32 v66, 1, v82
	s_mul_hi_u32 s27, s5, 0x3000
	s_mulk_i32 s5, 0x3000
	v_lshlrev_b32_e32 v67, 1, v82
	v_and_b32_e32 v66, 16, v66
	s_add_u32 s5, s96, s5
	v_and_b32_e32 v64, 0x5f, v82
	v_and_or_b32 v66, v67, s24, v66
	s_addc_u32 s27, s97, s27
	s_lshl_b64 s[6:7], s[6:7], 2
	v_mad_u32_u24 v64, v64, s25, v66
	s_add_u32 s28, s5, s6
	v_ashrrev_i32_e32 v78, 2, v82
	s_barrier
	ds_write_b128 v64, v[48:51]
	ds_write_b128 v64, v[52:55] offset:32
	ds_write_b128 v64, v[56:59] offset:64
	ds_write_b128 v64, v[60:63] offset:96
	ds_write_b128 v64, v[32:35] offset:128
	ds_write_b128 v64, v[36:39] offset:160
	ds_write_b128 v64, v[40:43] offset:192
	ds_write_b128 v64, v[44:47] offset:224
	ds_write_b128 v64, v[16:19] offset:33280
	ds_write_b128 v64, v[20:23] offset:33312
	ds_write_b128 v64, v[24:27] offset:33344
	ds_write_b128 v64, v[28:31] offset:33376
	ds_write_b128 v64, v[0:3] offset:33408
	ds_write_b128 v64, v[4:7] offset:33440
	ds_write_b128 v64, v[8:11] offset:33472
	ds_write_b128 v64, v[12:15] offset:33504
	s_addc_u32 s29, s27, s7
	v_lshlrev_b32_e32 v0, 4, v82
	v_and_b32_e32 v82, -16, v78
	s_add_u32 s6, s74, s6
	v_add_u32_e32 v16, s4, v82
	v_and_b32_e32 v64, 0x3f0, v0
	s_addc_u32 s7, s75, s7
	v_ashrrev_i32_e32 v17, 31, v16
	v_lshl_add_u64 v[14:15], s[6:7], 0, v[64:65]
	v_lshlrev_b64 v[2:3], 12, v[16:17]
	v_lshl_add_u64 v[4:5], v[14:15], 0, v[2:3]
	v_or_b32_e32 v2, 1, v16
	v_ashrrev_i32_e32 v3, 31, v2
	v_lshlrev_b64 v[2:3], 12, v[2:3]
	v_lshl_add_u64 v[6:7], v[14:15], 0, v[2:3]
	v_or_b32_e32 v2, 2, v16
	v_ashrrev_i32_e32 v3, 31, v2
	v_lshlrev_b64 v[2:3], 12, v[2:3]
	v_lshl_add_u64 v[8:9], v[14:15], 0, v[2:3]
	v_or_b32_e32 v2, 3, v16
	v_ashrrev_i32_e32 v3, 31, v2
	v_lshlrev_b64 v[2:3], 12, v[2:3]
	v_lshl_add_u64 v[0:1], s[28:29], 0, v[64:65]
	v_lshl_add_u64 v[10:11], v[14:15], 0, v[2:3]
	v_or_b32_e32 v2, 4, v16
	v_ashrrev_i32_e32 v3, 31, v2
	v_add_co_u32_e32 v0, vcc, s26, v0
	v_lshlrev_b64 v[2:3], 12, v[2:3]
	s_nop 0
	v_addc_co_u32_e32 v1, vcc, 0, v1, vcc
	s_waitcnt lgkmcnt(0)
	s_barrier
	v_lshl_add_u64 v[12:13], v[14:15], 0, v[2:3]
	global_load_dwordx4 v[0:3], v[0:1], off
	s_nop 0
	global_load_dwordx4 v[20:23], v[4:5], off
	v_or_b32_e32 v28, 6, v16
	global_load_dwordx4 v[24:27], v[6:7], off
	v_ashrrev_i32_e32 v29, 31, v28
	v_lshlrev_b64 v[32:33], 12, v[28:29]
	global_load_dwordx4 v[28:31], v[8:9], off
	v_or_b32_e32 v36, 7, v16
	v_ashrrev_i32_e32 v37, 31, v36
	v_lshl_add_u64 v[90:91], v[14:15], 0, v[32:33]
	global_load_dwordx4 v[32:35], v[10:11], off
	v_lshlrev_b64 v[36:37], 12, v[36:37]
	v_lshl_add_u64 v[92:93], v[14:15], 0, v[36:37]
	global_load_dwordx4 v[36:39], v[12:13], off
	v_or_b32_e32 v18, 5, v16
	v_ashrrev_i32_e32 v19, 31, v18
	v_or_b32_e32 v40, 8, v16
	v_lshlrev_b64 v[18:19], 12, v[18:19]
	v_ashrrev_i32_e32 v41, 31, v40
	v_lshl_add_u64 v[18:19], v[14:15], 0, v[18:19]
	v_lshlrev_b64 v[40:41], 12, v[40:41]
	v_or_b32_e32 v44, 9, v16
	v_lshl_add_u64 v[94:95], v[14:15], 0, v[40:41]
	global_load_dwordx4 v[40:43], v[18:19], off
	v_ashrrev_i32_e32 v45, 31, v44
	v_lshlrev_b64 v[48:49], 12, v[44:45]
	global_load_dwordx4 v[44:47], v[90:91], off
	v_or_b32_e32 v52, 10, v16
	v_ashrrev_i32_e32 v53, 31, v52
	v_lshl_add_u64 v[96:97], v[14:15], 0, v[48:49]
	global_load_dwordx4 v[48:51], v[92:93], off
	v_lshlrev_b64 v[52:53], 12, v[52:53]
	v_lshl_add_u64 v[98:99], v[14:15], 0, v[52:53]
	global_load_dwordx4 v[52:55], v[94:95], off
	v_or_b32_e32 v56, 11, v16
	v_ashrrev_i32_e32 v57, 31, v56
	v_lshlrev_b64 v[56:57], 12, v[56:57]
	v_or_b32_e32 v60, 12, v16
	v_lshl_add_u64 v[100:101], v[14:15], 0, v[56:57]
	global_load_dwordx4 v[56:59], v[96:97], off
	v_ashrrev_i32_e32 v61, 31, v60
	v_lshlrev_b64 v[66:67], 12, v[60:61]
	global_load_dwordx4 v[60:63], v[98:99], off
	v_or_b32_e32 v70, 13, v16
	v_ashrrev_i32_e32 v71, 31, v70
	v_lshl_add_u64 v[102:103], v[14:15], 0, v[66:67]
	global_load_dwordx4 v[66:69], v[100:101], off
	v_lshlrev_b64 v[70:71], 12, v[70:71]
	v_or_b32_e32 v16, 14, v16
	v_lshl_add_u64 v[104:105], v[14:15], 0, v[70:71]
	global_load_dwordx4 v[70:73], v[102:103], off
	v_ashrrev_i32_e32 v17, 31, v16
	v_lshlrev_b64 v[16:17], 12, v[16:17]
	v_or_b32_e32 v86, 15, v78
	v_lshl_add_u64 v[106:107], v[14:15], 0, v[16:17]
	v_add_u32_e32 v16, s4, v86
	v_ashrrev_i32_e32 v17, 31, v16
	v_lshlrev_b64 v[16:17], 12, v[16:17]
	global_load_dwordx4 v[74:77], v[104:105], off
	global_load_dwordx4 v[78:81], v[106:107], off
	v_lshl_add_u64 v[108:109], v[14:15], 0, v[16:17]
	global_load_dwordx4 v[14:17], v[108:109], off
	v_mad_u64_u32 v[110:111], s[4:5], v82, s25, v[64:65]
	ds_read_b128 v[82:85], v110
	v_mad_u64_u32 v[112:113], s[4:5], v86, s25, v[64:65]
	ds_read_b128 v[86:89], v110 offset:1040
	s_add_i32 s2, s2, s62
	s_add_i32 s16, s16, s15
	s_cmpk_lt_i32 s2, 0x300
	s_waitcnt vmcnt(15) lgkmcnt(1)
	v_pk_fma_f32 v[20:21], v[0:1], v[82:83], v[20:21]
	v_pk_fma_f32 v[22:23], v[2:3], v[84:85], v[22:23]
	global_store_dwordx4 v[4:5], v[20:23], off
	ds_read_b128 v[20:23], v110 offset:2080
	s_waitcnt vmcnt(15) lgkmcnt(1)
	v_pk_fma_f32 v[24:25], v[0:1], v[86:87], v[24:25]
	v_pk_fma_f32 v[26:27], v[2:3], v[88:89], v[26:27]
	global_store_dwordx4 v[6:7], v[24:27], off
	ds_read_b128 v[4:7], v110 offset:3120
	s_waitcnt vmcnt(15) lgkmcnt(1)
	v_pk_fma_f32 v[20:21], v[0:1], v[20:21], v[28:29]
	v_pk_fma_f32 v[22:23], v[2:3], v[22:23], v[30:31]
	global_store_dwordx4 v[8:9], v[20:23], off
	ds_read_b128 v[20:23], v110 offset:4160
	s_waitcnt vmcnt(15) lgkmcnt(1)
	v_pk_fma_f32 v[4:5], v[0:1], v[4:5], v[32:33]
	v_pk_fma_f32 v[6:7], v[2:3], v[6:7], v[34:35]
	global_store_dwordx4 v[10:11], v[4:7], off
	ds_read_b128 v[4:7], v110 offset:5200
	s_waitcnt vmcnt(15) lgkmcnt(1)
	v_pk_fma_f32 v[8:9], v[0:1], v[20:21], v[36:37]
	v_pk_fma_f32 v[10:11], v[2:3], v[22:23], v[38:39]
	global_store_dwordx4 v[12:13], v[8:11], off
	ds_read_b128 v[8:11], v110 offset:6240
	s_waitcnt vmcnt(15) lgkmcnt(1)
	v_pk_fma_f32 v[4:5], v[0:1], v[4:5], v[40:41]
	v_pk_fma_f32 v[6:7], v[2:3], v[6:7], v[42:43]
	global_store_dwordx4 v[18:19], v[4:7], off
	ds_read_b128 v[4:7], v110 offset:7280
	s_waitcnt vmcnt(15) lgkmcnt(1)
	v_pk_fma_f32 v[8:9], v[0:1], v[8:9], v[44:45]
	v_pk_fma_f32 v[10:11], v[2:3], v[10:11], v[46:47]
	global_store_dwordx4 v[90:91], v[8:11], off
	ds_read_b128 v[8:11], v110 offset:8320
	s_waitcnt vmcnt(15) lgkmcnt(1)
	v_pk_fma_f32 v[4:5], v[0:1], v[4:5], v[48:49]
	v_pk_fma_f32 v[6:7], v[2:3], v[6:7], v[50:51]
	global_store_dwordx4 v[92:93], v[4:7], off
	ds_read_b128 v[4:7], v110 offset:9360
	s_waitcnt vmcnt(15) lgkmcnt(1)
	v_pk_fma_f32 v[8:9], v[0:1], v[8:9], v[52:53]
	v_pk_fma_f32 v[10:11], v[2:3], v[10:11], v[54:55]
	global_store_dwordx4 v[94:95], v[8:11], off
	ds_read_b128 v[8:11], v110 offset:10400
	s_waitcnt vmcnt(15) lgkmcnt(1)
	v_pk_fma_f32 v[4:5], v[0:1], v[4:5], v[56:57]
	v_pk_fma_f32 v[6:7], v[2:3], v[6:7], v[58:59]
	global_store_dwordx4 v[96:97], v[4:7], off
	ds_read_b128 v[4:7], v110 offset:11440
	s_waitcnt vmcnt(15) lgkmcnt(1)
	v_pk_fma_f32 v[8:9], v[0:1], v[8:9], v[60:61]
	v_pk_fma_f32 v[10:11], v[2:3], v[10:11], v[62:63]
	global_store_dwordx4 v[98:99], v[8:11], off
	ds_read_b128 v[8:11], v110 offset:12480
	s_waitcnt vmcnt(15) lgkmcnt(1)
	v_pk_fma_f32 v[4:5], v[0:1], v[4:5], v[66:67]
	v_pk_fma_f32 v[6:7], v[2:3], v[6:7], v[68:69]
	global_store_dwordx4 v[100:101], v[4:7], off
	ds_read_b128 v[4:7], v110 offset:13520
	s_waitcnt vmcnt(15) lgkmcnt(1)
	v_pk_fma_f32 v[8:9], v[0:1], v[8:9], v[70:71]
	v_pk_fma_f32 v[10:11], v[2:3], v[10:11], v[72:73]
	global_store_dwordx4 v[102:103], v[8:11], off
	ds_read_b128 v[8:11], v110 offset:14560
	ds_read_b128 v[18:21], v112
	s_waitcnt vmcnt(15) lgkmcnt(2)
	v_pk_fma_f32 v[4:5], v[0:1], v[4:5], v[74:75]
	v_pk_fma_f32 v[6:7], v[2:3], v[6:7], v[76:77]
	global_store_dwordx4 v[104:105], v[4:7], off
	s_waitcnt vmcnt(15) lgkmcnt(1)
	s_nop 0
	v_pk_fma_f32 v[4:5], v[0:1], v[8:9], v[78:79]
	v_pk_fma_f32 v[6:7], v[2:3], v[10:11], v[80:81]
	s_waitcnt vmcnt(14) lgkmcnt(0)
	v_pk_fma_f32 v[0:1], v[0:1], v[18:19], v[14:15]
	v_pk_fma_f32 v[2:3], v[2:3], v[20:21], v[16:17]
	global_store_dwordx4 v[106:107], v[4:7], off
	global_store_dwordx4 v[108:109], v[0:3], off
	s_cbranch_scc0 .LBB0_884
